# RWKV scan: one counted lgkmcnt wait covers the b, k, v and w operands of a step (two s_waitcnt fewer per step)
# baseline (speedup 1.0000x reference)
.Lrwkv_scan_loop:
	s_waitcnt lgkmcnt(10)
	v_pk_mul_f32 v[148:149], v[184:185], v[112:113]
	v_pk_mul_f32 v[150:151], v[236:237], v[112:113]
	v_pk_fma_f32 v[148:149], v[186:187], v[114:115], v[148:149]
	v_pk_fma_f32 v[150:151], v[248:249], v[114:115], v[150:151]
	v_pk_fma_f32 v[148:149], v[188:189], v[116:117], v[148:149]
	v_pk_fma_f32 v[150:151], v[250:251], v[116:117], v[150:151]
	v_pk_fma_f32 v[148:149], v[190:191], v[118:119], v[148:149]
	v_pk_fma_f32 v[150:151], v[252:253], v[118:119], v[150:151]
	ds_read_b128 v[112:115], v222 offset:49408
	ds_read_b128 v[116:119], v222 offset:49424
	v_add_f32_e32 v152, v148, v149
	v_add_f32_e32 v153, v156, v157
	v_add_f32_e32 v154, v150, v151
	v_add_f32_e32 v155, v158, v159
	v_add_f32_dpp v152, v152, v152 quad_perm:[1,0,3,2] row_mask:0xf bank_mask:0xf bound_ctrl:1
	v_add_f32_dpp v153, v153, v153 quad_perm:[1,0,3,2] row_mask:0xf bank_mask:0xf bound_ctrl:1
	v_add_f32_dpp v154, v154, v154 quad_perm:[1,0,3,2] row_mask:0xf bank_mask:0xf bound_ctrl:1
	v_add_f32_dpp v155, v155, v155 quad_perm:[1,0,3,2] row_mask:0xf bank_mask:0xf bound_ctrl:1
	v_add_f32_dpp v152, v152, v152 quad_perm:[2,3,0,1] row_mask:0xf bank_mask:0xf bound_ctrl:1
	v_add_f32_dpp v153, v153, v153 quad_perm:[2,3,0,1] row_mask:0xf bank_mask:0xf bound_ctrl:1
	v_add_f32_dpp v154, v154, v154 quad_perm:[2,3,0,1] row_mask:0xf bank_mask:0xf bound_ctrl:1
	v_add_f32_dpp v155, v155, v155 quad_perm:[2,3,0,1] row_mask:0xf bank_mask:0xf bound_ctrl:1
	v_add_f32_dpp v152, v152, v152 row_half_mirror row_mask:0xf bank_mask:0xf bound_ctrl:1
	v_add_f32_dpp v153, v153, v153 row_half_mirror row_mask:0xf bank_mask:0xf bound_ctrl:1
	v_add_f32_dpp v154, v154, v154 row_half_mirror row_mask:0xf bank_mask:0xf bound_ctrl:1
	v_add_f32_dpp v155, v155, v155 row_half_mirror row_mask:0xf bank_mask:0xf bound_ctrl:1
	v_cndmask_b32_e64 v224, v224, v153, s[8:9]
	v_cndmask_b32_e64 v225, v225, v155, s[8:9]
	ds_write_b32 v227, v224
	ds_write_b32 v227, v225 offset:128
	s_waitcnt lgkmcnt(4)
	v_pk_mul_f32 v[160:161], v[120:121], v[152:153] op_sel_hi:[1,0] neg_lo:[0,1] neg_hi:[0,1]
	v_pk_mul_f32 v[168:169], v[120:121], v[154:155] op_sel_hi:[1,0] neg_lo:[0,1] neg_hi:[0,1]
	v_pk_mul_f32 v[162:163], v[122:123], v[152:153] op_sel_hi:[1,0] neg_lo:[0,1] neg_hi:[0,1]
	v_pk_mul_f32 v[170:171], v[122:123], v[154:155] op_sel_hi:[1,0] neg_lo:[0,1] neg_hi:[0,1]
	v_pk_mul_f32 v[164:165], v[124:125], v[152:153] op_sel_hi:[1,0] neg_lo:[0,1] neg_hi:[0,1]
	v_pk_mul_f32 v[172:173], v[124:125], v[154:155] op_sel_hi:[1,0] neg_lo:[0,1] neg_hi:[0,1]
	v_pk_mul_f32 v[166:167], v[126:127], v[152:153] op_sel_hi:[1,0] neg_lo:[0,1] neg_hi:[0,1]
	v_pk_mul_f32 v[174:175], v[126:127], v[154:155] op_sel_hi:[1,0] neg_lo:[0,1] neg_hi:[0,1]
	v_add_u32_e32 v227, s27, v217
	ds_read_b128 v[120:123], v223 offset:256
	ds_read_b128 v[124:127], v223 offset:272
	v_pk_fma_f32 v[160:161], v[144:145], v[128:129], v[160:161] op_sel_hi:[0,1,1]
	v_pk_fma_f32 v[168:169], v[146:147], v[128:129], v[168:169] op_sel_hi:[0,1,1]
	v_pk_fma_f32 v[162:163], v[144:145], v[130:131], v[162:163] op_sel_hi:[0,1,1]
	v_pk_fma_f32 v[170:171], v[146:147], v[130:131], v[170:171] op_sel_hi:[0,1,1]
	v_pk_fma_f32 v[164:165], v[144:145], v[132:133], v[164:165] op_sel_hi:[0,1,1]
	v_pk_fma_f32 v[172:173], v[146:147], v[132:133], v[172:173] op_sel_hi:[0,1,1]
	v_pk_fma_f32 v[166:167], v[144:145], v[134:135], v[166:167] op_sel_hi:[0,1,1]
	v_pk_fma_f32 v[174:175], v[146:147], v[134:135], v[174:175] op_sel_hi:[0,1,1]
	ds_read_b128 v[128:131], v222 offset:33024
	ds_read_b128 v[132:135], v222 offset:33040
	ds_read_b32 v144, v226 offset:256
	ds_read_b32 v146, v226 offset:384
	v_pk_fma_f32 v[184:185], v[184:185], v[104:105], v[160:161]
	v_pk_fma_f32 v[236:237], v[236:237], v[104:105], v[168:169]
	v_pk_fma_f32 v[186:187], v[186:187], v[106:107], v[162:163]
	v_pk_fma_f32 v[248:249], v[248:249], v[106:107], v[170:171]
	v_pk_fma_f32 v[188:189], v[188:189], v[108:109], v[164:165]
	v_pk_fma_f32 v[250:251], v[250:251], v[108:109], v[172:173]
	v_pk_fma_f32 v[190:191], v[190:191], v[110:111], v[166:167]
	v_pk_fma_f32 v[252:253], v[252:253], v[110:111], v[174:175]
	ds_read_b128 v[104:107], v222 offset:16640
	ds_read_b128 v[108:111], v222 offset:16656
	s_waitcnt lgkmcnt(10)
	v_pk_mul_f32 v[156:157], v[184:185], v[136:137]
	v_pk_mul_f32 v[158:159], v[236:237], v[136:137]
	v_pk_fma_f32 v[156:157], v[186:187], v[138:139], v[156:157]
	v_pk_fma_f32 v[158:159], v[248:249], v[138:139], v[158:159]
	v_pk_fma_f32 v[156:157], v[188:189], v[140:141], v[156:157]
	v_pk_fma_f32 v[158:159], v[250:251], v[140:141], v[158:159]
	v_pk_fma_f32 v[156:157], v[190:191], v[142:143], v[156:157]
	v_pk_fma_f32 v[158:159], v[252:253], v[142:143], v[158:159]
	ds_read_b128 v[136:139], v222 offset:256
	ds_read_b128 v[140:143], v222 offset:272
	s_waitcnt lgkmcnt(10)
	v_pk_mul_f32 v[148:149], v[184:185], v[112:113]
	v_pk_mul_f32 v[150:151], v[236:237], v[112:113]
	v_pk_fma_f32 v[148:149], v[186:187], v[114:115], v[148:149]
	v_pk_fma_f32 v[150:151], v[248:249], v[114:115], v[150:151]
	v_pk_fma_f32 v[148:149], v[188:189], v[116:117], v[148:149]
	v_pk_fma_f32 v[150:151], v[250:251], v[116:117], v[150:151]
	v_pk_fma_f32 v[148:149], v[190:191], v[118:119], v[148:149]
	v_pk_fma_f32 v[150:151], v[252:253], v[118:119], v[150:151]
	ds_read_b128 v[112:115], v222 offset:49664
	ds_read_b128 v[116:119], v222 offset:49680
	v_add_f32_e32 v152, v148, v149
	v_add_f32_e32 v153, v156, v157
	v_add_f32_e32 v154, v150, v151
	v_add_f32_e32 v155, v158, v159
	v_add_f32_dpp v152, v152, v152 quad_perm:[1,0,3,2] row_mask:0xf bank_mask:0xf bound_ctrl:1
	v_add_f32_dpp v153, v153, v153 quad_perm:[1,0,3,2] row_mask:0xf bank_mask:0xf bound_ctrl:1
	v_add_f32_dpp v154, v154, v154 quad_perm:[1,0,3,2] row_mask:0xf bank_mask:0xf bound_ctrl:1
	v_add_f32_dpp v155, v155, v155 quad_perm:[1,0,3,2] row_mask:0xf bank_mask:0xf bound_ctrl:1
	v_add_f32_dpp v152, v152, v152 quad_perm:[2,3,0,1] row_mask:0xf bank_mask:0xf bound_ctrl:1
	v_add_f32_dpp v153, v153, v153 quad_perm:[2,3,0,1] row_mask:0xf bank_mask:0xf bound_ctrl:1
	v_add_f32_dpp v154, v154, v154 quad_perm:[2,3,0,1] row_mask:0xf bank_mask:0xf bound_ctrl:1
	v_add_f32_dpp v155, v155, v155 quad_perm:[2,3,0,1] row_mask:0xf bank_mask:0xf bound_ctrl:1
	v_add_f32_dpp v152, v152, v152 row_half_mirror row_mask:0xf bank_mask:0xf bound_ctrl:1
	v_add_f32_dpp v153, v153, v153 row_half_mirror row_mask:0xf bank_mask:0xf bound_ctrl:1
	v_add_f32_dpp v154, v154, v154 row_half_mirror row_mask:0xf bank_mask:0xf bound_ctrl:1
	v_add_f32_dpp v155, v155, v155 row_half_mirror row_mask:0xf bank_mask:0xf bound_ctrl:1
	v_cndmask_b32_e64 v224, v224, v153, s[6:7]
	v_cndmask_b32_e64 v225, v225, v155, s[6:7]
	s_waitcnt lgkmcnt(4)
	v_pk_mul_f32 v[160:161], v[120:121], v[152:153] op_sel_hi:[1,0] neg_lo:[0,1] neg_hi:[0,1]
	v_pk_mul_f32 v[168:169], v[120:121], v[154:155] op_sel_hi:[1,0] neg_lo:[0,1] neg_hi:[0,1]
	v_pk_mul_f32 v[162:163], v[122:123], v[152:153] op_sel_hi:[1,0] neg_lo:[0,1] neg_hi:[0,1]
	v_pk_mul_f32 v[170:171], v[122:123], v[154:155] op_sel_hi:[1,0] neg_lo:[0,1] neg_hi:[0,1]
	v_pk_mul_f32 v[164:165], v[124:125], v[152:153] op_sel_hi:[1,0] neg_lo:[0,1] neg_hi:[0,1]
	v_pk_mul_f32 v[172:173], v[124:125], v[154:155] op_sel_hi:[1,0] neg_lo:[0,1] neg_hi:[0,1]
	v_pk_mul_f32 v[166:167], v[126:127], v[152:153] op_sel_hi:[1,0] neg_lo:[0,1] neg_hi:[0,1]
	v_pk_mul_f32 v[174:175], v[126:127], v[154:155] op_sel_hi:[1,0] neg_lo:[0,1] neg_hi:[0,1]
	ds_read_b128 v[120:123], v223 offset:512
	ds_read_b128 v[124:127], v223 offset:528
	v_pk_fma_f32 v[160:161], v[144:145], v[128:129], v[160:161] op_sel_hi:[0,1,1]
	v_pk_fma_f32 v[168:169], v[146:147], v[128:129], v[168:169] op_sel_hi:[0,1,1]
	v_pk_fma_f32 v[162:163], v[144:145], v[130:131], v[162:163] op_sel_hi:[0,1,1]
	v_pk_fma_f32 v[170:171], v[146:147], v[130:131], v[170:171] op_sel_hi:[0,1,1]
	v_pk_fma_f32 v[164:165], v[144:145], v[132:133], v[164:165] op_sel_hi:[0,1,1]
	v_pk_fma_f32 v[172:173], v[146:147], v[132:133], v[172:173] op_sel_hi:[0,1,1]
	v_pk_fma_f32 v[166:167], v[144:145], v[134:135], v[166:167] op_sel_hi:[0,1,1]
	v_pk_fma_f32 v[174:175], v[146:147], v[134:135], v[174:175] op_sel_hi:[0,1,1]
	ds_read_b128 v[128:131], v222 offset:33280
	ds_read_b128 v[132:135], v222 offset:33296
	ds_read_b32 v144, v226 offset:512
	ds_read_b32 v146, v226 offset:640
	v_pk_fma_f32 v[184:185], v[184:185], v[104:105], v[160:161]
	v_pk_fma_f32 v[236:237], v[236:237], v[104:105], v[168:169]
	v_pk_fma_f32 v[186:187], v[186:187], v[106:107], v[162:163]
	v_pk_fma_f32 v[248:249], v[248:249], v[106:107], v[170:171]
	v_pk_fma_f32 v[188:189], v[188:189], v[108:109], v[164:165]
	v_pk_fma_f32 v[250:251], v[250:251], v[108:109], v[172:173]
	v_pk_fma_f32 v[190:191], v[190:191], v[110:111], v[166:167]
	v_pk_fma_f32 v[252:253], v[252:253], v[110:111], v[174:175]
	ds_read_b128 v[104:107], v222 offset:16896
	ds_read_b128 v[108:111], v222 offset:16912
	s_waitcnt lgkmcnt(10)
	v_pk_mul_f32 v[156:157], v[184:185], v[136:137]
	v_pk_mul_f32 v[158:159], v[236:237], v[136:137]
	v_pk_fma_f32 v[156:157], v[186:187], v[138:139], v[156:157]
	v_pk_fma_f32 v[158:159], v[248:249], v[138:139], v[158:159]
	v_pk_fma_f32 v[156:157], v[188:189], v[140:141], v[156:157]
	v_pk_fma_f32 v[158:159], v[250:251], v[140:141], v[158:159]
	v_pk_fma_f32 v[156:157], v[190:191], v[142:143], v[156:157]
	v_pk_fma_f32 v[158:159], v[252:253], v[142:143], v[158:159]
	ds_read_b128 v[136:139], v222 offset:512
	ds_read_b128 v[140:143], v222 offset:528
	s_waitcnt lgkmcnt(10)
	v_pk_mul_f32 v[148:149], v[184:185], v[112:113]
	v_pk_mul_f32 v[150:151], v[236:237], v[112:113]
	v_pk_fma_f32 v[148:149], v[186:187], v[114:115], v[148:149]
	v_pk_fma_f32 v[150:151], v[248:249], v[114:115], v[150:151]
	v_pk_fma_f32 v[148:149], v[188:189], v[116:117], v[148:149]
	v_pk_fma_f32 v[150:151], v[250:251], v[116:117], v[150:151]
	v_pk_fma_f32 v[148:149], v[190:191], v[118:119], v[148:149]
	v_pk_fma_f32 v[150:151], v[252:253], v[118:119], v[150:151]
	ds_read_b128 v[112:115], v222 offset:49920
	ds_read_b128 v[116:119], v222 offset:49936
	v_add_f32_e32 v152, v148, v149
	v_add_f32_e32 v153, v156, v157
	v_add_f32_e32 v154, v150, v151
	v_add_f32_e32 v155, v158, v159
	v_add_f32_dpp v152, v152, v152 quad_perm:[1,0,3,2] row_mask:0xf bank_mask:0xf bound_ctrl:1
	v_add_f32_dpp v153, v153, v153 quad_perm:[1,0,3,2] row_mask:0xf bank_mask:0xf bound_ctrl:1
	v_add_f32_dpp v154, v154, v154 quad_perm:[1,0,3,2] row_mask:0xf bank_mask:0xf bound_ctrl:1
	v_add_f32_dpp v155, v155, v155 quad_perm:[1,0,3,2] row_mask:0xf bank_mask:0xf bound_ctrl:1
	v_add_f32_dpp v152, v152, v152 quad_perm:[2,3,0,1] row_mask:0xf bank_mask:0xf bound_ctrl:1
	v_add_f32_dpp v153, v153, v153 quad_perm:[2,3,0,1] row_mask:0xf bank_mask:0xf bound_ctrl:1
	v_add_f32_dpp v154, v154, v154 quad_perm:[2,3,0,1] row_mask:0xf bank_mask:0xf bound_ctrl:1
	v_add_f32_dpp v155, v155, v155 quad_perm:[2,3,0,1] row_mask:0xf bank_mask:0xf bound_ctrl:1
	v_add_f32_dpp v152, v152, v152 row_half_mirror row_mask:0xf bank_mask:0xf bound_ctrl:1
	v_add_f32_dpp v153, v153, v153 row_half_mirror row_mask:0xf bank_mask:0xf bound_ctrl:1
	v_add_f32_dpp v154, v154, v154 row_half_mirror row_mask:0xf bank_mask:0xf bound_ctrl:1
	v_add_f32_dpp v155, v155, v155 row_half_mirror row_mask:0xf bank_mask:0xf bound_ctrl:1
	v_cndmask_b32_e64 v224, v224, v153, s[10:11]
	v_cndmask_b32_e64 v225, v225, v155, s[10:11]
	s_waitcnt lgkmcnt(4)
	v_pk_mul_f32 v[160:161], v[120:121], v[152:153] op_sel_hi:[1,0] neg_lo:[0,1] neg_hi:[0,1]
	v_pk_mul_f32 v[168:169], v[120:121], v[154:155] op_sel_hi:[1,0] neg_lo:[0,1] neg_hi:[0,1]
	v_pk_mul_f32 v[162:163], v[122:123], v[152:153] op_sel_hi:[1,0] neg_lo:[0,1] neg_hi:[0,1]
	v_pk_mul_f32 v[170:171], v[122:123], v[154:155] op_sel_hi:[1,0] neg_lo:[0,1] neg_hi:[0,1]
	v_pk_mul_f32 v[164:165], v[124:125], v[152:153] op_sel_hi:[1,0] neg_lo:[0,1] neg_hi:[0,1]
	v_pk_mul_f32 v[172:173], v[124:125], v[154:155] op_sel_hi:[1,0] neg_lo:[0,1] neg_hi:[0,1]
	v_pk_mul_f32 v[166:167], v[126:127], v[152:153] op_sel_hi:[1,0] neg_lo:[0,1] neg_hi:[0,1]
	v_pk_mul_f32 v[174:175], v[126:127], v[154:155] op_sel_hi:[1,0] neg_lo:[0,1] neg_hi:[0,1]
	ds_read_b128 v[120:123], v223 offset:768
	ds_read_b128 v[124:127], v223 offset:784
	v_pk_fma_f32 v[160:161], v[144:145], v[128:129], v[160:161] op_sel_hi:[0,1,1]
	v_pk_fma_f32 v[168:169], v[146:147], v[128:129], v[168:169] op_sel_hi:[0,1,1]
	v_pk_fma_f32 v[162:163], v[144:145], v[130:131], v[162:163] op_sel_hi:[0,1,1]
	v_pk_fma_f32 v[170:171], v[146:147], v[130:131], v[170:171] op_sel_hi:[0,1,1]
	v_pk_fma_f32 v[164:165], v[144:145], v[132:133], v[164:165] op_sel_hi:[0,1,1]
	v_pk_fma_f32 v[172:173], v[146:147], v[132:133], v[172:173] op_sel_hi:[0,1,1]
	v_pk_fma_f32 v[166:167], v[144:145], v[134:135], v[166:167] op_sel_hi:[0,1,1]
	v_pk_fma_f32 v[174:175], v[146:147], v[134:135], v[174:175] op_sel_hi:[0,1,1]
	ds_read_b128 v[128:131], v222 offset:33536
	ds_read_b128 v[132:135], v222 offset:33552
	ds_read_b32 v144, v226 offset:768
	ds_read_b32 v146, v226 offset:896
	v_pk_fma_f32 v[184:185], v[184:185], v[104:105], v[160:161]
	v_pk_fma_f32 v[236:237], v[236:237], v[104:105], v[168:169]
	v_pk_fma_f32 v[186:187], v[186:187], v[106:107], v[162:163]
	v_pk_fma_f32 v[248:249], v[248:249], v[106:107], v[170:171]
	v_pk_fma_f32 v[188:189], v[188:189], v[108:109], v[164:165]
	v_pk_fma_f32 v[250:251], v[250:251], v[108:109], v[172:173]
	v_pk_fma_f32 v[190:191], v[190:191], v[110:111], v[166:167]
	v_pk_fma_f32 v[252:253], v[252:253], v[110:111], v[174:175]
	ds_read_b128 v[104:107], v222 offset:17152
	ds_read_b128 v[108:111], v222 offset:17168
	s_waitcnt lgkmcnt(10)
	v_pk_mul_f32 v[156:157], v[184:185], v[136:137]
	v_pk_mul_f32 v[158:159], v[236:237], v[136:137]
	v_pk_fma_f32 v[156:157], v[186:187], v[138:139], v[156:157]
	v_pk_fma_f32 v[158:159], v[248:249], v[138:139], v[158:159]
	v_pk_fma_f32 v[156:157], v[188:189], v[140:141], v[156:157]
	v_pk_fma_f32 v[158:159], v[250:251], v[140:141], v[158:159]
	v_pk_fma_f32 v[156:157], v[190:191], v[142:143], v[156:157]
	v_pk_fma_f32 v[158:159], v[252:253], v[142:143], v[158:159]
	ds_read_b128 v[136:139], v222 offset:768
	ds_read_b128 v[140:143], v222 offset:784
	s_waitcnt lgkmcnt(10)
	v_pk_mul_f32 v[148:149], v[184:185], v[112:113]
	v_pk_mul_f32 v[150:151], v[236:237], v[112:113]
	v_pk_fma_f32 v[148:149], v[186:187], v[114:115], v[148:149]
	v_pk_fma_f32 v[150:151], v[248:249], v[114:115], v[150:151]
	v_pk_fma_f32 v[148:149], v[188:189], v[116:117], v[148:149]
	v_pk_fma_f32 v[150:151], v[250:251], v[116:117], v[150:151]
	v_pk_fma_f32 v[148:149], v[190:191], v[118:119], v[148:149]
	v_pk_fma_f32 v[150:151], v[252:253], v[118:119], v[150:151]
	ds_read_b128 v[112:115], v222 offset:50176
	ds_read_b128 v[116:119], v222 offset:50192
	v_add_f32_e32 v152, v148, v149
	v_add_f32_e32 v153, v156, v157
	v_add_f32_e32 v154, v150, v151
	v_add_f32_e32 v155, v158, v159
	v_add_f32_dpp v152, v152, v152 quad_perm:[1,0,3,2] row_mask:0xf bank_mask:0xf bound_ctrl:1
	v_add_f32_dpp v153, v153, v153 quad_perm:[1,0,3,2] row_mask:0xf bank_mask:0xf bound_ctrl:1
	v_add_f32_dpp v154, v154, v154 quad_perm:[1,0,3,2] row_mask:0xf bank_mask:0xf bound_ctrl:1
	v_add_f32_dpp v155, v155, v155 quad_perm:[1,0,3,2] row_mask:0xf bank_mask:0xf bound_ctrl:1
	v_add_f32_dpp v152, v152, v152 quad_perm:[2,3,0,1] row_mask:0xf bank_mask:0xf bound_ctrl:1
	v_add_f32_dpp v153, v153, v153 quad_perm:[2,3,0,1] row_mask:0xf bank_mask:0xf bound_ctrl:1
	v_add_f32_dpp v154, v154, v154 quad_perm:[2,3,0,1] row_mask:0xf bank_mask:0xf bound_ctrl:1
	v_add_f32_dpp v155, v155, v155 quad_perm:[2,3,0,1] row_mask:0xf bank_mask:0xf bound_ctrl:1
	v_add_f32_dpp v152, v152, v152 row_half_mirror row_mask:0xf bank_mask:0xf bound_ctrl:1
	v_add_f32_dpp v153, v153, v153 row_half_mirror row_mask:0xf bank_mask:0xf bound_ctrl:1
	v_add_f32_dpp v154, v154, v154 row_half_mirror row_mask:0xf bank_mask:0xf bound_ctrl:1
	v_add_f32_dpp v155, v155, v155 row_half_mirror row_mask:0xf bank_mask:0xf bound_ctrl:1
	v_cndmask_b32_e64 v224, v224, v153, s[12:13]
	v_cndmask_b32_e64 v225, v225, v155, s[12:13]
	s_waitcnt lgkmcnt(4)
	v_pk_mul_f32 v[160:161], v[120:121], v[152:153] op_sel_hi:[1,0] neg_lo:[0,1] neg_hi:[0,1]
	v_pk_mul_f32 v[168:169], v[120:121], v[154:155] op_sel_hi:[1,0] neg_lo:[0,1] neg_hi:[0,1]
	v_pk_mul_f32 v[162:163], v[122:123], v[152:153] op_sel_hi:[1,0] neg_lo:[0,1] neg_hi:[0,1]
	v_pk_mul_f32 v[170:171], v[122:123], v[154:155] op_sel_hi:[1,0] neg_lo:[0,1] neg_hi:[0,1]
	v_pk_mul_f32 v[164:165], v[124:125], v[152:153] op_sel_hi:[1,0] neg_lo:[0,1] neg_hi:[0,1]
	v_pk_mul_f32 v[172:173], v[124:125], v[154:155] op_sel_hi:[1,0] neg_lo:[0,1] neg_hi:[0,1]
	v_pk_mul_f32 v[166:167], v[126:127], v[152:153] op_sel_hi:[1,0] neg_lo:[0,1] neg_hi:[0,1]
	v_pk_mul_f32 v[174:175], v[126:127], v[154:155] op_sel_hi:[1,0] neg_lo:[0,1] neg_hi:[0,1]
	ds_read_b128 v[120:123], v223 offset:1024
	ds_read_b128 v[124:127], v223 offset:1040
	v_pk_fma_f32 v[160:161], v[144:145], v[128:129], v[160:161] op_sel_hi:[0,1,1]
	v_pk_fma_f32 v[168:169], v[146:147], v[128:129], v[168:169] op_sel_hi:[0,1,1]
	v_pk_fma_f32 v[162:163], v[144:145], v[130:131], v[162:163] op_sel_hi:[0,1,1]
	v_pk_fma_f32 v[170:171], v[146:147], v[130:131], v[170:171] op_sel_hi:[0,1,1]
	v_pk_fma_f32 v[164:165], v[144:145], v[132:133], v[164:165] op_sel_hi:[0,1,1]
	v_pk_fma_f32 v[172:173], v[146:147], v[132:133], v[172:173] op_sel_hi:[0,1,1]
	v_pk_fma_f32 v[166:167], v[144:145], v[134:135], v[166:167] op_sel_hi:[0,1,1]
	v_pk_fma_f32 v[174:175], v[146:147], v[134:135], v[174:175] op_sel_hi:[0,1,1]
	ds_read_b128 v[128:131], v222 offset:33792
	ds_read_b128 v[132:135], v222 offset:33808
	ds_read_b32 v144, v226 offset:1024
	ds_read_b32 v146, v226 offset:1152
	v_pk_fma_f32 v[184:185], v[184:185], v[104:105], v[160:161]
	v_pk_fma_f32 v[236:237], v[236:237], v[104:105], v[168:169]
	v_pk_fma_f32 v[186:187], v[186:187], v[106:107], v[162:163]
	v_pk_fma_f32 v[248:249], v[248:249], v[106:107], v[170:171]
	v_pk_fma_f32 v[188:189], v[188:189], v[108:109], v[164:165]
	v_pk_fma_f32 v[250:251], v[250:251], v[108:109], v[172:173]
	v_pk_fma_f32 v[190:191], v[190:191], v[110:111], v[166:167]
	v_pk_fma_f32 v[252:253], v[252:253], v[110:111], v[174:175]
	ds_read_b128 v[104:107], v222 offset:17408
	ds_read_b128 v[108:111], v222 offset:17424
	s_waitcnt lgkmcnt(10)
	v_pk_mul_f32 v[156:157], v[184:185], v[136:137]
	v_pk_mul_f32 v[158:159], v[236:237], v[136:137]
	v_pk_fma_f32 v[156:157], v[186:187], v[138:139], v[156:157]
	v_pk_fma_f32 v[158:159], v[248:249], v[138:139], v[158:159]
	v_pk_fma_f32 v[156:157], v[188:189], v[140:141], v[156:157]
	v_pk_fma_f32 v[158:159], v[250:251], v[140:141], v[158:159]
	v_pk_fma_f32 v[156:157], v[190:191], v[142:143], v[156:157]
	v_pk_fma_f32 v[158:159], v[252:253], v[142:143], v[158:159]
	ds_read_b128 v[136:139], v222 offset:1024
	ds_read_b128 v[140:143], v222 offset:1040
	s_waitcnt lgkmcnt(10)
	v_pk_mul_f32 v[148:149], v[184:185], v[112:113]
	v_pk_mul_f32 v[150:151], v[236:237], v[112:113]
	v_pk_fma_f32 v[148:149], v[186:187], v[114:115], v[148:149]
	v_pk_fma_f32 v[150:151], v[248:249], v[114:115], v[150:151]
	v_pk_fma_f32 v[148:149], v[188:189], v[116:117], v[148:149]
	v_pk_fma_f32 v[150:151], v[250:251], v[116:117], v[150:151]
	v_pk_fma_f32 v[148:149], v[190:191], v[118:119], v[148:149]
	v_pk_fma_f32 v[150:151], v[252:253], v[118:119], v[150:151]
	ds_read_b128 v[112:115], v222 offset:50432
	ds_read_b128 v[116:119], v222 offset:50448
	v_add_f32_e32 v152, v148, v149
	v_add_f32_e32 v153, v156, v157
	v_add_f32_e32 v154, v150, v151
	v_add_f32_e32 v155, v158, v159
	v_add_f32_dpp v152, v152, v152 quad_perm:[1,0,3,2] row_mask:0xf bank_mask:0xf bound_ctrl:1
	v_add_f32_dpp v153, v153, v153 quad_perm:[1,0,3,2] row_mask:0xf bank_mask:0xf bound_ctrl:1
	v_add_f32_dpp v154, v154, v154 quad_perm:[1,0,3,2] row_mask:0xf bank_mask:0xf bound_ctrl:1
	v_add_f32_dpp v155, v155, v155 quad_perm:[1,0,3,2] row_mask:0xf bank_mask:0xf bound_ctrl:1
	v_add_f32_dpp v152, v152, v152 quad_perm:[2,3,0,1] row_mask:0xf bank_mask:0xf bound_ctrl:1
	v_add_f32_dpp v153, v153, v153 quad_perm:[2,3,0,1] row_mask:0xf bank_mask:0xf bound_ctrl:1
	v_add_f32_dpp v154, v154, v154 quad_perm:[2,3,0,1] row_mask:0xf bank_mask:0xf bound_ctrl:1
	v_add_f32_dpp v155, v155, v155 quad_perm:[2,3,0,1] row_mask:0xf bank_mask:0xf bound_ctrl:1
	v_add_f32_dpp v152, v152, v152 row_half_mirror row_mask:0xf bank_mask:0xf bound_ctrl:1
	v_add_f32_dpp v153, v153, v153 row_half_mirror row_mask:0xf bank_mask:0xf bound_ctrl:1
	v_add_f32_dpp v154, v154, v154 row_half_mirror row_mask:0xf bank_mask:0xf bound_ctrl:1
	v_add_f32_dpp v155, v155, v155 row_half_mirror row_mask:0xf bank_mask:0xf bound_ctrl:1
	v_cndmask_b32_e64 v224, v224, v153, s[14:15]
	v_cndmask_b32_e64 v225, v225, v155, s[14:15]
	s_waitcnt lgkmcnt(4)
	v_pk_mul_f32 v[160:161], v[120:121], v[152:153] op_sel_hi:[1,0] neg_lo:[0,1] neg_hi:[0,1]
	v_pk_mul_f32 v[168:169], v[120:121], v[154:155] op_sel_hi:[1,0] neg_lo:[0,1] neg_hi:[0,1]
	v_pk_mul_f32 v[162:163], v[122:123], v[152:153] op_sel_hi:[1,0] neg_lo:[0,1] neg_hi:[0,1]
	v_pk_mul_f32 v[170:171], v[122:123], v[154:155] op_sel_hi:[1,0] neg_lo:[0,1] neg_hi:[0,1]
	v_pk_mul_f32 v[164:165], v[124:125], v[152:153] op_sel_hi:[1,0] neg_lo:[0,1] neg_hi:[0,1]
	v_pk_mul_f32 v[172:173], v[124:125], v[154:155] op_sel_hi:[1,0] neg_lo:[0,1] neg_hi:[0,1]
	v_pk_mul_f32 v[166:167], v[126:127], v[152:153] op_sel_hi:[1,0] neg_lo:[0,1] neg_hi:[0,1]
	v_pk_mul_f32 v[174:175], v[126:127], v[154:155] op_sel_hi:[1,0] neg_lo:[0,1] neg_hi:[0,1]
	ds_read_b128 v[120:123], v223 offset:1280
	ds_read_b128 v[124:127], v223 offset:1296
	v_pk_fma_f32 v[160:161], v[144:145], v[128:129], v[160:161] op_sel_hi:[0,1,1]
	v_pk_fma_f32 v[168:169], v[146:147], v[128:129], v[168:169] op_sel_hi:[0,1,1]
	v_pk_fma_f32 v[162:163], v[144:145], v[130:131], v[162:163] op_sel_hi:[0,1,1]
	v_pk_fma_f32 v[170:171], v[146:147], v[130:131], v[170:171] op_sel_hi:[0,1,1]
	v_pk_fma_f32 v[164:165], v[144:145], v[132:133], v[164:165] op_sel_hi:[0,1,1]
	v_pk_fma_f32 v[172:173], v[146:147], v[132:133], v[172:173] op_sel_hi:[0,1,1]
	v_pk_fma_f32 v[166:167], v[144:145], v[134:135], v[166:167] op_sel_hi:[0,1,1]
	v_pk_fma_f32 v[174:175], v[146:147], v[134:135], v[174:175] op_sel_hi:[0,1,1]
	ds_read_b128 v[128:131], v222 offset:34048
	ds_read_b128 v[132:135], v222 offset:34064
	ds_read_b32 v144, v226 offset:1280
	ds_read_b32 v146, v226 offset:1408
	v_pk_fma_f32 v[184:185], v[184:185], v[104:105], v[160:161]
	v_pk_fma_f32 v[236:237], v[236:237], v[104:105], v[168:169]
	v_pk_fma_f32 v[186:187], v[186:187], v[106:107], v[162:163]
	v_pk_fma_f32 v[248:249], v[248:249], v[106:107], v[170:171]
	v_pk_fma_f32 v[188:189], v[188:189], v[108:109], v[164:165]
	v_pk_fma_f32 v[250:251], v[250:251], v[108:109], v[172:173]
	v_pk_fma_f32 v[190:191], v[190:191], v[110:111], v[166:167]
	v_pk_fma_f32 v[252:253], v[252:253], v[110:111], v[174:175]
	ds_read_b128 v[104:107], v222 offset:17664
	ds_read_b128 v[108:111], v222 offset:17680
	s_waitcnt lgkmcnt(10)
	v_pk_mul_f32 v[156:157], v[184:185], v[136:137]
	v_pk_mul_f32 v[158:159], v[236:237], v[136:137]
	v_pk_fma_f32 v[156:157], v[186:187], v[138:139], v[156:157]
	v_pk_fma_f32 v[158:159], v[248:249], v[138:139], v[158:159]
	v_pk_fma_f32 v[156:157], v[188:189], v[140:141], v[156:157]
	v_pk_fma_f32 v[158:159], v[250:251], v[140:141], v[158:159]
	v_pk_fma_f32 v[156:157], v[190:191], v[142:143], v[156:157]
	v_pk_fma_f32 v[158:159], v[252:253], v[142:143], v[158:159]
	ds_read_b128 v[136:139], v222 offset:1280
	ds_read_b128 v[140:143], v222 offset:1296
	s_waitcnt lgkmcnt(10)
	v_pk_mul_f32 v[148:149], v[184:185], v[112:113]
	v_pk_mul_f32 v[150:151], v[236:237], v[112:113]
	v_pk_fma_f32 v[148:149], v[186:187], v[114:115], v[148:149]
	v_pk_fma_f32 v[150:151], v[248:249], v[114:115], v[150:151]
	v_pk_fma_f32 v[148:149], v[188:189], v[116:117], v[148:149]
	v_pk_fma_f32 v[150:151], v[250:251], v[116:117], v[150:151]
	v_pk_fma_f32 v[148:149], v[190:191], v[118:119], v[148:149]
	v_pk_fma_f32 v[150:151], v[252:253], v[118:119], v[150:151]
	ds_read_b128 v[112:115], v222 offset:50688
	ds_read_b128 v[116:119], v222 offset:50704
	v_add_f32_e32 v152, v148, v149
	v_add_f32_e32 v153, v156, v157
	v_add_f32_e32 v154, v150, v151
	v_add_f32_e32 v155, v158, v159
	v_add_f32_dpp v152, v152, v152 quad_perm:[1,0,3,2] row_mask:0xf bank_mask:0xf bound_ctrl:1
	v_add_f32_dpp v153, v153, v153 quad_perm:[1,0,3,2] row_mask:0xf bank_mask:0xf bound_ctrl:1
	v_add_f32_dpp v154, v154, v154 quad_perm:[1,0,3,2] row_mask:0xf bank_mask:0xf bound_ctrl:1
	v_add_f32_dpp v155, v155, v155 quad_perm:[1,0,3,2] row_mask:0xf bank_mask:0xf bound_ctrl:1
	v_add_f32_dpp v152, v152, v152 quad_perm:[2,3,0,1] row_mask:0xf bank_mask:0xf bound_ctrl:1
	v_add_f32_dpp v153, v153, v153 quad_perm:[2,3,0,1] row_mask:0xf bank_mask:0xf bound_ctrl:1
	v_add_f32_dpp v154, v154, v154 quad_perm:[2,3,0,1] row_mask:0xf bank_mask:0xf bound_ctrl:1
	v_add_f32_dpp v155, v155, v155 quad_perm:[2,3,0,1] row_mask:0xf bank_mask:0xf bound_ctrl:1
	v_add_f32_dpp v152, v152, v152 row_half_mirror row_mask:0xf bank_mask:0xf bound_ctrl:1
	v_add_f32_dpp v153, v153, v153 row_half_mirror row_mask:0xf bank_mask:0xf bound_ctrl:1
	v_add_f32_dpp v154, v154, v154 row_half_mirror row_mask:0xf bank_mask:0xf bound_ctrl:1
	v_add_f32_dpp v155, v155, v155 row_half_mirror row_mask:0xf bank_mask:0xf bound_ctrl:1
	v_cndmask_b32_e64 v224, v224, v153, s[16:17]
	v_cndmask_b32_e64 v225, v225, v155, s[16:17]
	s_waitcnt lgkmcnt(4)
	v_pk_mul_f32 v[160:161], v[120:121], v[152:153] op_sel_hi:[1,0] neg_lo:[0,1] neg_hi:[0,1]
	v_pk_mul_f32 v[168:169], v[120:121], v[154:155] op_sel_hi:[1,0] neg_lo:[0,1] neg_hi:[0,1]
	v_pk_mul_f32 v[162:163], v[122:123], v[152:153] op_sel_hi:[1,0] neg_lo:[0,1] neg_hi:[0,1]
	v_pk_mul_f32 v[170:171], v[122:123], v[154:155] op_sel_hi:[1,0] neg_lo:[0,1] neg_hi:[0,1]
	v_pk_mul_f32 v[164:165], v[124:125], v[152:153] op_sel_hi:[1,0] neg_lo:[0,1] neg_hi:[0,1]
	v_pk_mul_f32 v[172:173], v[124:125], v[154:155] op_sel_hi:[1,0] neg_lo:[0,1] neg_hi:[0,1]
	v_pk_mul_f32 v[166:167], v[126:127], v[152:153] op_sel_hi:[1,0] neg_lo:[0,1] neg_hi:[0,1]
	v_pk_mul_f32 v[174:175], v[126:127], v[154:155] op_sel_hi:[1,0] neg_lo:[0,1] neg_hi:[0,1]
	ds_read_b128 v[120:123], v223 offset:1536
	ds_read_b128 v[124:127], v223 offset:1552
	v_pk_fma_f32 v[160:161], v[144:145], v[128:129], v[160:161] op_sel_hi:[0,1,1]
	v_pk_fma_f32 v[168:169], v[146:147], v[128:129], v[168:169] op_sel_hi:[0,1,1]
	v_pk_fma_f32 v[162:163], v[144:145], v[130:131], v[162:163] op_sel_hi:[0,1,1]
	v_pk_fma_f32 v[170:171], v[146:147], v[130:131], v[170:171] op_sel_hi:[0,1,1]
	v_pk_fma_f32 v[164:165], v[144:145], v[132:133], v[164:165] op_sel_hi:[0,1,1]
	v_pk_fma_f32 v[172:173], v[146:147], v[132:133], v[172:173] op_sel_hi:[0,1,1]
	v_pk_fma_f32 v[166:167], v[144:145], v[134:135], v[166:167] op_sel_hi:[0,1,1]
	v_pk_fma_f32 v[174:175], v[146:147], v[134:135], v[174:175] op_sel_hi:[0,1,1]
	ds_read_b128 v[128:131], v222 offset:34304
	ds_read_b128 v[132:135], v222 offset:34320
	ds_read_b32 v144, v226 offset:1536
	ds_read_b32 v146, v226 offset:1664
	v_pk_fma_f32 v[184:185], v[184:185], v[104:105], v[160:161]
	v_pk_fma_f32 v[236:237], v[236:237], v[104:105], v[168:169]
	v_pk_fma_f32 v[186:187], v[186:187], v[106:107], v[162:163]
	v_pk_fma_f32 v[248:249], v[248:249], v[106:107], v[170:171]
	v_pk_fma_f32 v[188:189], v[188:189], v[108:109], v[164:165]
	v_pk_fma_f32 v[250:251], v[250:251], v[108:109], v[172:173]
	v_pk_fma_f32 v[190:191], v[190:191], v[110:111], v[166:167]
	v_pk_fma_f32 v[252:253], v[252:253], v[110:111], v[174:175]
	ds_read_b128 v[104:107], v222 offset:17920
	ds_read_b128 v[108:111], v222 offset:17936
	s_waitcnt lgkmcnt(10)
	v_pk_mul_f32 v[156:157], v[184:185], v[136:137]
	v_pk_mul_f32 v[158:159], v[236:237], v[136:137]
	v_pk_fma_f32 v[156:157], v[186:187], v[138:139], v[156:157]
	v_pk_fma_f32 v[158:159], v[248:249], v[138:139], v[158:159]
	v_pk_fma_f32 v[156:157], v[188:189], v[140:141], v[156:157]
	v_pk_fma_f32 v[158:159], v[250:251], v[140:141], v[158:159]
	v_pk_fma_f32 v[156:157], v[190:191], v[142:143], v[156:157]
	v_pk_fma_f32 v[158:159], v[252:253], v[142:143], v[158:159]
	ds_read_b128 v[136:139], v222 offset:1536
	ds_read_b128 v[140:143], v222 offset:1552
	s_waitcnt lgkmcnt(10)
	v_pk_mul_f32 v[148:149], v[184:185], v[112:113]
	v_pk_mul_f32 v[150:151], v[236:237], v[112:113]
	v_pk_fma_f32 v[148:149], v[186:187], v[114:115], v[148:149]
	v_pk_fma_f32 v[150:151], v[248:249], v[114:115], v[150:151]
	v_pk_fma_f32 v[148:149], v[188:189], v[116:117], v[148:149]
	v_pk_fma_f32 v[150:151], v[250:251], v[116:117], v[150:151]
	v_pk_fma_f32 v[148:149], v[190:191], v[118:119], v[148:149]
	v_pk_fma_f32 v[150:151], v[252:253], v[118:119], v[150:151]
	ds_read_b128 v[112:115], v222 offset:50944
	ds_read_b128 v[116:119], v222 offset:50960
	v_add_f32_e32 v152, v148, v149
	v_add_f32_e32 v153, v156, v157
	v_add_f32_e32 v154, v150, v151
	v_add_f32_e32 v155, v158, v159
	v_add_f32_dpp v152, v152, v152 quad_perm:[1,0,3,2] row_mask:0xf bank_mask:0xf bound_ctrl:1
	v_add_f32_dpp v153, v153, v153 quad_perm:[1,0,3,2] row_mask:0xf bank_mask:0xf bound_ctrl:1
	v_add_f32_dpp v154, v154, v154 quad_perm:[1,0,3,2] row_mask:0xf bank_mask:0xf bound_ctrl:1
	v_add_f32_dpp v155, v155, v155 quad_perm:[1,0,3,2] row_mask:0xf bank_mask:0xf bound_ctrl:1
	v_add_f32_dpp v152, v152, v152 quad_perm:[2,3,0,1] row_mask:0xf bank_mask:0xf bound_ctrl:1
	v_add_f32_dpp v153, v153, v153 quad_perm:[2,3,0,1] row_mask:0xf bank_mask:0xf bound_ctrl:1
	v_add_f32_dpp v154, v154, v154 quad_perm:[2,3,0,1] row_mask:0xf bank_mask:0xf bound_ctrl:1
	v_add_f32_dpp v155, v155, v155 quad_perm:[2,3,0,1] row_mask:0xf bank_mask:0xf bound_ctrl:1
	v_add_f32_dpp v152, v152, v152 row_half_mirror row_mask:0xf bank_mask:0xf bound_ctrl:1
	v_add_f32_dpp v153, v153, v153 row_half_mirror row_mask:0xf bank_mask:0xf bound_ctrl:1
	v_add_f32_dpp v154, v154, v154 row_half_mirror row_mask:0xf bank_mask:0xf bound_ctrl:1
	v_add_f32_dpp v155, v155, v155 row_half_mirror row_mask:0xf bank_mask:0xf bound_ctrl:1
	v_cndmask_b32_e64 v224, v224, v153, s[18:19]
	v_cndmask_b32_e64 v225, v225, v155, s[18:19]
	s_waitcnt lgkmcnt(4)
	v_pk_mul_f32 v[160:161], v[120:121], v[152:153] op_sel_hi:[1,0] neg_lo:[0,1] neg_hi:[0,1]
	v_pk_mul_f32 v[168:169], v[120:121], v[154:155] op_sel_hi:[1,0] neg_lo:[0,1] neg_hi:[0,1]
	v_pk_mul_f32 v[162:163], v[122:123], v[152:153] op_sel_hi:[1,0] neg_lo:[0,1] neg_hi:[0,1]
	v_pk_mul_f32 v[170:171], v[122:123], v[154:155] op_sel_hi:[1,0] neg_lo:[0,1] neg_hi:[0,1]
	v_pk_mul_f32 v[164:165], v[124:125], v[152:153] op_sel_hi:[1,0] neg_lo:[0,1] neg_hi:[0,1]
	v_pk_mul_f32 v[172:173], v[124:125], v[154:155] op_sel_hi:[1,0] neg_lo:[0,1] neg_hi:[0,1]
	v_pk_mul_f32 v[166:167], v[126:127], v[152:153] op_sel_hi:[1,0] neg_lo:[0,1] neg_hi:[0,1]
	v_pk_mul_f32 v[174:175], v[126:127], v[154:155] op_sel_hi:[1,0] neg_lo:[0,1] neg_hi:[0,1]
	ds_read_b128 v[120:123], v223 offset:1792
	ds_read_b128 v[124:127], v223 offset:1808
	v_pk_fma_f32 v[160:161], v[144:145], v[128:129], v[160:161] op_sel_hi:[0,1,1]
	v_pk_fma_f32 v[168:169], v[146:147], v[128:129], v[168:169] op_sel_hi:[0,1,1]
	v_pk_fma_f32 v[162:163], v[144:145], v[130:131], v[162:163] op_sel_hi:[0,1,1]
	v_pk_fma_f32 v[170:171], v[146:147], v[130:131], v[170:171] op_sel_hi:[0,1,1]
	v_pk_fma_f32 v[164:165], v[144:145], v[132:133], v[164:165] op_sel_hi:[0,1,1]
	v_pk_fma_f32 v[172:173], v[146:147], v[132:133], v[172:173] op_sel_hi:[0,1,1]
	v_pk_fma_f32 v[166:167], v[144:145], v[134:135], v[166:167] op_sel_hi:[0,1,1]
	v_pk_fma_f32 v[174:175], v[146:147], v[134:135], v[174:175] op_sel_hi:[0,1,1]
	ds_read_b128 v[128:131], v222 offset:34560
	ds_read_b128 v[132:135], v222 offset:34576
	ds_read_b32 v144, v226 offset:1792
	ds_read_b32 v146, v226 offset:1920
	v_pk_fma_f32 v[184:185], v[184:185], v[104:105], v[160:161]
	v_pk_fma_f32 v[236:237], v[236:237], v[104:105], v[168:169]
	v_pk_fma_f32 v[186:187], v[186:187], v[106:107], v[162:163]
	v_pk_fma_f32 v[248:249], v[248:249], v[106:107], v[170:171]
	v_pk_fma_f32 v[188:189], v[188:189], v[108:109], v[164:165]
	v_pk_fma_f32 v[250:251], v[250:251], v[108:109], v[172:173]
	v_pk_fma_f32 v[190:191], v[190:191], v[110:111], v[166:167]
	v_pk_fma_f32 v[252:253], v[252:253], v[110:111], v[174:175]
	ds_read_b128 v[104:107], v222 offset:18176
	ds_read_b128 v[108:111], v222 offset:18192
	s_waitcnt lgkmcnt(10)
	v_pk_mul_f32 v[156:157], v[184:185], v[136:137]
	v_pk_mul_f32 v[158:159], v[236:237], v[136:137]
	v_pk_fma_f32 v[156:157], v[186:187], v[138:139], v[156:157]
	v_pk_fma_f32 v[158:159], v[248:249], v[138:139], v[158:159]
	v_pk_fma_f32 v[156:157], v[188:189], v[140:141], v[156:157]
	v_pk_fma_f32 v[158:159], v[250:251], v[140:141], v[158:159]
	v_pk_fma_f32 v[156:157], v[190:191], v[142:143], v[156:157]
	v_pk_fma_f32 v[158:159], v[252:253], v[142:143], v[158:159]
	ds_read_b128 v[136:139], v222 offset:1792
	ds_read_b128 v[140:143], v222 offset:1808
	s_waitcnt lgkmcnt(10)
	v_pk_mul_f32 v[148:149], v[184:185], v[112:113]
	v_pk_mul_f32 v[150:151], v[236:237], v[112:113]
	v_pk_fma_f32 v[148:149], v[186:187], v[114:115], v[148:149]
	v_pk_fma_f32 v[150:151], v[248:249], v[114:115], v[150:151]
	v_pk_fma_f32 v[148:149], v[188:189], v[116:117], v[148:149]
	v_pk_fma_f32 v[150:151], v[250:251], v[116:117], v[150:151]
	v_pk_fma_f32 v[148:149], v[190:191], v[118:119], v[148:149]
	v_pk_fma_f32 v[150:151], v[252:253], v[118:119], v[150:151]
	ds_read_b128 v[112:115], v222 offset:51200
	ds_read_b128 v[116:119], v222 offset:51216
	v_add_f32_e32 v152, v148, v149
	v_add_f32_e32 v153, v156, v157
	v_add_f32_e32 v154, v150, v151
	v_add_f32_e32 v155, v158, v159
	v_add_f32_dpp v152, v152, v152 quad_perm:[1,0,3,2] row_mask:0xf bank_mask:0xf bound_ctrl:1
	v_add_f32_dpp v153, v153, v153 quad_perm:[1,0,3,2] row_mask:0xf bank_mask:0xf bound_ctrl:1
	v_add_f32_dpp v154, v154, v154 quad_perm:[1,0,3,2] row_mask:0xf bank_mask:0xf bound_ctrl:1
	v_add_f32_dpp v155, v155, v155 quad_perm:[1,0,3,2] row_mask:0xf bank_mask:0xf bound_ctrl:1
	v_add_f32_dpp v152, v152, v152 quad_perm:[2,3,0,1] row_mask:0xf bank_mask:0xf bound_ctrl:1
	v_add_f32_dpp v153, v153, v153 quad_perm:[2,3,0,1] row_mask:0xf bank_mask:0xf bound_ctrl:1
	v_add_f32_dpp v154, v154, v154 quad_perm:[2,3,0,1] row_mask:0xf bank_mask:0xf bound_ctrl:1
	v_add_f32_dpp v155, v155, v155 quad_perm:[2,3,0,1] row_mask:0xf bank_mask:0xf bound_ctrl:1
	v_add_f32_dpp v152, v152, v152 row_half_mirror row_mask:0xf bank_mask:0xf bound_ctrl:1
	v_add_f32_dpp v153, v153, v153 row_half_mirror row_mask:0xf bank_mask:0xf bound_ctrl:1
	v_add_f32_dpp v154, v154, v154 row_half_mirror row_mask:0xf bank_mask:0xf bound_ctrl:1
	v_add_f32_dpp v155, v155, v155 row_half_mirror row_mask:0xf bank_mask:0xf bound_ctrl:1
	v_cndmask_b32_e64 v224, v224, v153, s[20:21]
	v_cndmask_b32_e64 v225, v225, v155, s[20:21]
	s_waitcnt lgkmcnt(4)
	v_pk_mul_f32 v[160:161], v[120:121], v[152:153] op_sel_hi:[1,0] neg_lo:[0,1] neg_hi:[0,1]
	v_pk_mul_f32 v[168:169], v[120:121], v[154:155] op_sel_hi:[1,0] neg_lo:[0,1] neg_hi:[0,1]
	v_pk_mul_f32 v[162:163], v[122:123], v[152:153] op_sel_hi:[1,0] neg_lo:[0,1] neg_hi:[0,1]
	v_pk_mul_f32 v[170:171], v[122:123], v[154:155] op_sel_hi:[1,0] neg_lo:[0,1] neg_hi:[0,1]
	v_pk_mul_f32 v[164:165], v[124:125], v[152:153] op_sel_hi:[1,0] neg_lo:[0,1] neg_hi:[0,1]
	v_pk_mul_f32 v[172:173], v[124:125], v[154:155] op_sel_hi:[1,0] neg_lo:[0,1] neg_hi:[0,1]
	v_pk_mul_f32 v[166:167], v[126:127], v[152:153] op_sel_hi:[1,0] neg_lo:[0,1] neg_hi:[0,1]
	v_pk_mul_f32 v[174:175], v[126:127], v[154:155] op_sel_hi:[1,0] neg_lo:[0,1] neg_hi:[0,1]
	ds_read_b128 v[120:123], v223 offset:2048
	ds_read_b128 v[124:127], v223 offset:2064
	v_pk_fma_f32 v[160:161], v[144:145], v[128:129], v[160:161] op_sel_hi:[0,1,1]
	v_pk_fma_f32 v[168:169], v[146:147], v[128:129], v[168:169] op_sel_hi:[0,1,1]
	v_pk_fma_f32 v[162:163], v[144:145], v[130:131], v[162:163] op_sel_hi:[0,1,1]
	v_pk_fma_f32 v[170:171], v[146:147], v[130:131], v[170:171] op_sel_hi:[0,1,1]
	v_pk_fma_f32 v[164:165], v[144:145], v[132:133], v[164:165] op_sel_hi:[0,1,1]
	v_pk_fma_f32 v[172:173], v[146:147], v[132:133], v[172:173] op_sel_hi:[0,1,1]
	v_pk_fma_f32 v[166:167], v[144:145], v[134:135], v[166:167] op_sel_hi:[0,1,1]
	v_pk_fma_f32 v[174:175], v[146:147], v[134:135], v[174:175] op_sel_hi:[0,1,1]
	ds_read_b128 v[128:131], v222 offset:34816
	ds_read_b128 v[132:135], v222 offset:34832
	ds_read_b32 v144, v226 offset:2048
	ds_read_b32 v146, v226 offset:2176
	v_pk_fma_f32 v[184:185], v[184:185], v[104:105], v[160:161]
	v_pk_fma_f32 v[236:237], v[236:237], v[104:105], v[168:169]
	v_pk_fma_f32 v[186:187], v[186:187], v[106:107], v[162:163]
	v_pk_fma_f32 v[248:249], v[248:249], v[106:107], v[170:171]
	v_pk_fma_f32 v[188:189], v[188:189], v[108:109], v[164:165]
	v_pk_fma_f32 v[250:251], v[250:251], v[108:109], v[172:173]
	v_pk_fma_f32 v[190:191], v[190:191], v[110:111], v[166:167]
	v_pk_fma_f32 v[252:253], v[252:253], v[110:111], v[174:175]
	ds_read_b128 v[104:107], v222 offset:18432
	ds_read_b128 v[108:111], v222 offset:18448
	s_waitcnt lgkmcnt(10)
	v_pk_mul_f32 v[156:157], v[184:185], v[136:137]
	v_pk_mul_f32 v[158:159], v[236:237], v[136:137]
	v_pk_fma_f32 v[156:157], v[186:187], v[138:139], v[156:157]
	v_pk_fma_f32 v[158:159], v[248:249], v[138:139], v[158:159]
	v_pk_fma_f32 v[156:157], v[188:189], v[140:141], v[156:157]
	v_pk_fma_f32 v[158:159], v[250:251], v[140:141], v[158:159]
	v_pk_fma_f32 v[156:157], v[190:191], v[142:143], v[156:157]
	v_pk_fma_f32 v[158:159], v[252:253], v[142:143], v[158:159]
	ds_read_b128 v[136:139], v222 offset:2048
	ds_read_b128 v[140:143], v222 offset:2064
	s_addk_i32 s27, 0x800
	v_add_u32_e32 v222, s27, v177
	v_add_u32_e32 v223, s27, v197
	v_add_u32_e32 v226, s27, v216
	s_cmpk_lg_u32 s27, 0x4000
	s_cbranch_scc1 .Lrwkv_scan_loop
	v_add_f32_e32 v153, v156, v157
	v_add_f32_e32 v155, v158, v159
	s_nop 1
	v_add_f32_dpp v153, v153, v153 quad_perm:[1,0,3,2] row_mask:0xf bank_mask:0xf bound_ctrl:1
	v_add_f32_dpp v155, v155, v155 quad_perm:[1,0,3,2] row_mask:0xf bank_mask:0xf bound_ctrl:1
	s_nop 1
	v_add_f32_dpp v153, v153, v153 quad_perm:[2,3,0,1] row_mask:0xf bank_mask:0xf bound_ctrl:1
	v_add_f32_dpp v155, v155, v155 quad_perm:[2,3,0,1] row_mask:0xf bank_mask:0xf bound_ctrl:1
	s_nop 1
	v_add_f32_dpp v153, v153, v153 row_half_mirror row_mask:0xf bank_mask:0xf bound_ctrl:1
	v_add_f32_dpp v155, v155, v155 row_half_mirror row_mask:0xf bank_mask:0xf bound_ctrl:1
	v_cndmask_b32_e64 v224, v224, v153, s[8:9]
	v_cndmask_b32_e64 v225, v225, v155, s[8:9]
	ds_write_b32 v227, v224
	ds_write_b32 v227, v225 offset:128
	s_waitcnt lgkmcnt(0)
	s_branch .LBB0_263
